# scan recurrence block: per-lane LDS address bases hoisted out of the chunk loop into persistent registers
# speedup vs baseline: 1.0079x; 1.0079x over previous
.LBB0_544:
	s_and_b32 s2, s65, 0xfffff000
	s_lshl_b32 s50, s50, 1
	v_add_u32_e32 v141, s2, v123
	v_or_b32_e32 v142, s2, v139
	s_add_u32 s2, s36, s50
	s_addc_u32 s3, s37, 0
	s_lshl_b32 s90, s5, 5
	s_lshl_b32 s5, s5, 6
	s_add_u32 s2, s2, s5
	s_addc_u32 s3, s3, 0
	v_mov_b32_e32 v93, v1
	s_lshl_b32 s4, s4, 2
	v_mov_b32_e32 v2, v1
	v_mov_b32_e32 v3, v1
	v_lshl_add_u64 v[106:107], s[2:3], 0, v[92:93]
	v_cmp_eq_u32_e64 s[2:3], 0, v16
	s_add_u32 s52, s38, s4
	v_mov_b32_e32 v0, v1
	v_mov_b64_e32 v[18:19], v[2:3]
	v_mov_b64_e32 v[22:23], v[2:3]
	s_mov_b32 s91, 0
	s_addc_u32 s53, s39, 0
	v_mov_b64_e32 v[16:17], v[0:1]
	v_mov_b64_e32 v[20:21], v[0:1]
	s_mov_b32 s89, s60
	s_mov_b32 s92, 0
	v_mbcnt_lo_u32_b32 v190, -1, 0
	v_mbcnt_hi_u32_b32 v190, -1, v190
	v_and_b32_e32 v191, 15, v190
	v_lshrrev_b32_e32 v192, 4, v190
	v_and_b32_e32 v193, 1, v190
	v_lshl_add_u32 v192, v192, 1, v193
	v_lshlrev_b32_e32 v194, 4, v191
	s_lshl_b32 s4, s90, 2
	s_add_i32 s4, s4, s59
	v_lshl_add_u32 v195, v192, 2, s4
	v_lshrrev_b32_e32 v191, 1, v191
	v_lshlrev_b32_e32 v191, 2, v191
	s_lshl_b32 s4, s59, 3
	v_lshl_add_u32 v196, v192, 5, v191
	v_add_u32_e32 v196, s4, v196
	s_waitcnt vmcnt(0) lgkmcnt(0)
	s_barrier
	s_branch .LBB0_547
.LBB0_545:
	s_mul_i32 s4, s93, 0x6000
	s_lshl_b32 s5, s93, 14
	v_add_u32_e32 v2, s4, v194
	v_add_u32_e32 v3, s4, v195
	v_add_u32_e32 v0, s5, v196
	v_xor_b32_e32 v53, 4, v3
	ds_read_b128 v[24:27], v2 offset:16384
	ds_read_b32 v44, v3 offset:12288
	ds_read_b32 v45, v53 offset:12288
	ds_read_b128 v[36:39], v2 offset:8192
	ds_read_b128 v[28:31], v2 offset:4096
	ds_read_b128 v[32:35], v2 offset:20480
	ds_read_b128 v[40:43], v2 offset:0
	ds_read_b128 v[144:147], v2 offset:16640
	ds_read_b32 v164, v3 offset:12544
	ds_read_b32 v165, v53 offset:12544
	ds_read_b128 v[156:159], v2 offset:8448
	ds_read_b128 v[148:151], v2 offset:4352
	ds_read_b128 v[152:155], v2 offset:20736
	s_waitcnt lgkmcnt(6)
	v_pk_mul_f32 v[46:47], v[16:17], v[24:25] op_sel_hi:[1,0]
	v_pk_fma_f32 v[46:47], v[18:19], v[24:25], v[46:47] op_sel:[0,1,0] op_sel_hi:[1,1,1]
	v_pk_fma_f32 v[46:47], v[20:21], v[26:27], v[46:47] op_sel_hi:[1,0,1]
	v_pk_fma_f32 v[46:47], v[22:23], v[26:27], v[46:47] op_sel:[0,1,0] op_sel_hi:[1,1,1]
	ds_read_b128 v[160:163], v2 offset:256
	v_pk_mul_f32 v[168:169], v[44:45], v[36:37] op_sel_hi:[1,0]
	v_add_f32_dpp v48, v47, v46 quad_perm:[1,0,3,2] row_mask:0xf bank_mask:0xf bound_ctrl:1
	v_pk_mul_f32 v[170:171], v[44:45], v[36:37] op_sel:[0,1] op_sel_hi:[1,1]
	s_nop 0
	v_add_f32_dpp v48, v48, v48 quad_perm:[2,3,0,1] row_mask:0xf bank_mask:0xf bound_ctrl:1
	v_pk_mul_f32 v[172:173], v[44:45], v[38:39] op_sel_hi:[1,0]
	v_pk_mul_f32 v[174:175], v[44:45], v[38:39] op_sel:[0,1] op_sel_hi:[1,1]
	v_add_f32_dpp v48, v48, v48 row_ror:4 row_mask:0xf bank_mask:0xf bound_ctrl:1
	v_pk_fma_f32 v[168:169], v[16:17], v[28:29], v[168:169] op_sel_hi:[1,0,1]
	v_pk_fma_f32 v[170:171], v[18:19], v[28:29], v[170:171] op_sel:[0,1,0] op_sel_hi:[1,1,1]
	v_add_f32_dpp v48, v48, v48 row_ror:8 row_mask:0xf bank_mask:0xf bound_ctrl:1
	v_pk_fma_f32 v[172:173], v[20:21], v[30:31], v[172:173] op_sel_hi:[1,0,1]
	v_pk_fma_f32 v[174:175], v[22:23], v[30:31], v[174:175] op_sel:[0,1,0] op_sel_hi:[1,1,1]
	v_mov_b32_dpp v49, v48 quad_perm:[1,0,3,2] row_mask:0xf bank_mask:0xf bound_ctrl:1
	v_pk_fma_f32 v[16:17], v[48:49], v[32:33], v[168:169] op_sel_hi:[1,0,1] neg_lo:[0,1,0] neg_hi:[0,1,0]
	v_pk_fma_f32 v[18:19], v[48:49], v[32:33], v[170:171] op_sel:[0,1,0] op_sel_hi:[1,1,1] neg_lo:[0,1,0] neg_hi:[0,1,0]
	v_pk_fma_f32 v[20:21], v[48:49], v[34:35], v[172:173] op_sel_hi:[1,0,1] neg_lo:[0,1,0] neg_hi:[0,1,0]
	v_pk_fma_f32 v[22:23], v[48:49], v[34:35], v[174:175] op_sel:[0,1,0] op_sel_hi:[1,1,1] neg_lo:[0,1,0] neg_hi:[0,1,0]
	ds_read_b128 v[24:27], v2 offset:16896
	ds_read_b32 v44, v3 offset:12800
	ds_read_b32 v45, v53 offset:12800
	ds_read_b128 v[36:39], v2 offset:8704
	ds_read_b128 v[28:31], v2 offset:4608
	ds_read_b128 v[32:35], v2 offset:20992
	s_waitcnt lgkmcnt(6)
	v_pk_mul_f32 v[46:47], v[16:17], v[144:145] op_sel_hi:[1,0]
	v_pk_mul_f32 v[50:51], v[16:17], v[40:41] op_sel_hi:[1,0]
	v_pk_fma_f32 v[46:47], v[18:19], v[144:145], v[46:47] op_sel:[0,1,0] op_sel_hi:[1,1,1]
	v_pk_fma_f32 v[50:51], v[18:19], v[40:41], v[50:51] op_sel:[0,1,0] op_sel_hi:[1,1,1]
	v_pk_fma_f32 v[46:47], v[20:21], v[146:147], v[46:47] op_sel_hi:[1,0,1]
	v_pk_fma_f32 v[50:51], v[20:21], v[42:43], v[50:51] op_sel_hi:[1,0,1]
	v_pk_fma_f32 v[46:47], v[22:23], v[146:147], v[46:47] op_sel:[0,1,0] op_sel_hi:[1,1,1]
	v_pk_fma_f32 v[50:51], v[22:23], v[42:43], v[50:51] op_sel:[0,1,0] op_sel_hi:[1,1,1]
	ds_read_b128 v[40:43], v2 offset:512
	v_pk_mul_f32 v[168:169], v[164:165], v[156:157] op_sel_hi:[1,0]
	v_add_f32_dpp v48, v47, v46 quad_perm:[1,0,3,2] row_mask:0xf bank_mask:0xf bound_ctrl:1
	v_add_f32_dpp v52, v51, v50 quad_perm:[1,0,3,2] row_mask:0xf bank_mask:0xf bound_ctrl:1
	v_pk_mul_f32 v[170:171], v[164:165], v[156:157] op_sel:[0,1] op_sel_hi:[1,1]
	v_add_f32_dpp v48, v48, v48 quad_perm:[2,3,0,1] row_mask:0xf bank_mask:0xf bound_ctrl:1
	ds_write_b32 v0, v52 offset:49152
	v_pk_mul_f32 v[172:173], v[164:165], v[158:159] op_sel_hi:[1,0]
	v_pk_mul_f32 v[174:175], v[164:165], v[158:159] op_sel:[0,1] op_sel_hi:[1,1]
	v_add_f32_dpp v48, v48, v48 row_ror:4 row_mask:0xf bank_mask:0xf bound_ctrl:1
	v_pk_fma_f32 v[168:169], v[16:17], v[148:149], v[168:169] op_sel_hi:[1,0,1]
	v_pk_fma_f32 v[170:171], v[18:19], v[148:149], v[170:171] op_sel:[0,1,0] op_sel_hi:[1,1,1]
	v_add_f32_dpp v48, v48, v48 row_ror:8 row_mask:0xf bank_mask:0xf bound_ctrl:1
	v_pk_fma_f32 v[172:173], v[20:21], v[150:151], v[172:173] op_sel_hi:[1,0,1]
	v_pk_fma_f32 v[174:175], v[22:23], v[150:151], v[174:175] op_sel:[0,1,0] op_sel_hi:[1,1,1]
	v_mov_b32_dpp v49, v48 quad_perm:[1,0,3,2] row_mask:0xf bank_mask:0xf bound_ctrl:1
	v_pk_fma_f32 v[16:17], v[48:49], v[152:153], v[168:169] op_sel_hi:[1,0,1] neg_lo:[0,1,0] neg_hi:[0,1,0]
	v_pk_fma_f32 v[18:19], v[48:49], v[152:153], v[170:171] op_sel:[0,1,0] op_sel_hi:[1,1,1] neg_lo:[0,1,0] neg_hi:[0,1,0]
	v_pk_fma_f32 v[20:21], v[48:49], v[154:155], v[172:173] op_sel_hi:[1,0,1] neg_lo:[0,1,0] neg_hi:[0,1,0]
	v_pk_fma_f32 v[22:23], v[48:49], v[154:155], v[174:175] op_sel:[0,1,0] op_sel_hi:[1,1,1] neg_lo:[0,1,0] neg_hi:[0,1,0]
	ds_read_b128 v[144:147], v2 offset:17152
	ds_read_b32 v164, v3 offset:13056
	ds_read_b32 v165, v53 offset:13056
	ds_read_b128 v[156:159], v2 offset:8960
	ds_read_b128 v[148:151], v2 offset:4864
	ds_read_b128 v[152:155], v2 offset:21248
	s_waitcnt lgkmcnt(7)
	v_pk_mul_f32 v[46:47], v[16:17], v[24:25] op_sel_hi:[1,0]
	v_pk_mul_f32 v[50:51], v[16:17], v[160:161] op_sel_hi:[1,0]
	v_pk_fma_f32 v[46:47], v[18:19], v[24:25], v[46:47] op_sel:[0,1,0] op_sel_hi:[1,1,1]
	v_pk_fma_f32 v[50:51], v[18:19], v[160:161], v[50:51] op_sel:[0,1,0] op_sel_hi:[1,1,1]
	v_pk_fma_f32 v[46:47], v[20:21], v[26:27], v[46:47] op_sel_hi:[1,0,1]
	v_pk_fma_f32 v[50:51], v[20:21], v[162:163], v[50:51] op_sel_hi:[1,0,1]
	v_pk_fma_f32 v[46:47], v[22:23], v[26:27], v[46:47] op_sel:[0,1,0] op_sel_hi:[1,1,1]
	v_pk_fma_f32 v[50:51], v[22:23], v[162:163], v[50:51] op_sel:[0,1,0] op_sel_hi:[1,1,1]
	ds_read_b128 v[160:163], v2 offset:768
	v_pk_mul_f32 v[168:169], v[44:45], v[36:37] op_sel_hi:[1,0]
	v_add_f32_dpp v48, v47, v46 quad_perm:[1,0,3,2] row_mask:0xf bank_mask:0xf bound_ctrl:1
	v_add_f32_dpp v52, v51, v50 quad_perm:[1,0,3,2] row_mask:0xf bank_mask:0xf bound_ctrl:1
	v_pk_mul_f32 v[170:171], v[44:45], v[36:37] op_sel:[0,1] op_sel_hi:[1,1]
	v_add_f32_dpp v48, v48, v48 quad_perm:[2,3,0,1] row_mask:0xf bank_mask:0xf bound_ctrl:1
	ds_write_b32 v0, v52 offset:50176
	v_pk_mul_f32 v[172:173], v[44:45], v[38:39] op_sel_hi:[1,0]
	v_pk_mul_f32 v[174:175], v[44:45], v[38:39] op_sel:[0,1] op_sel_hi:[1,1]
	v_add_f32_dpp v48, v48, v48 row_ror:4 row_mask:0xf bank_mask:0xf bound_ctrl:1
	v_pk_fma_f32 v[168:169], v[16:17], v[28:29], v[168:169] op_sel_hi:[1,0,1]
	v_pk_fma_f32 v[170:171], v[18:19], v[28:29], v[170:171] op_sel:[0,1,0] op_sel_hi:[1,1,1]
	v_add_f32_dpp v48, v48, v48 row_ror:8 row_mask:0xf bank_mask:0xf bound_ctrl:1
	v_pk_fma_f32 v[172:173], v[20:21], v[30:31], v[172:173] op_sel_hi:[1,0,1]
	v_pk_fma_f32 v[174:175], v[22:23], v[30:31], v[174:175] op_sel:[0,1,0] op_sel_hi:[1,1,1]
	v_mov_b32_dpp v49, v48 quad_perm:[1,0,3,2] row_mask:0xf bank_mask:0xf bound_ctrl:1
	v_pk_fma_f32 v[16:17], v[48:49], v[32:33], v[168:169] op_sel_hi:[1,0,1] neg_lo:[0,1,0] neg_hi:[0,1,0]
	v_pk_fma_f32 v[18:19], v[48:49], v[32:33], v[170:171] op_sel:[0,1,0] op_sel_hi:[1,1,1] neg_lo:[0,1,0] neg_hi:[0,1,0]
	v_pk_fma_f32 v[20:21], v[48:49], v[34:35], v[172:173] op_sel_hi:[1,0,1] neg_lo:[0,1,0] neg_hi:[0,1,0]
	v_pk_fma_f32 v[22:23], v[48:49], v[34:35], v[174:175] op_sel:[0,1,0] op_sel_hi:[1,1,1] neg_lo:[0,1,0] neg_hi:[0,1,0]
	ds_read_b128 v[24:27], v2 offset:17408
	ds_read_b32 v44, v3 offset:13312
	ds_read_b32 v45, v53 offset:13312
	ds_read_b128 v[36:39], v2 offset:9216
	ds_read_b128 v[28:31], v2 offset:5120
	ds_read_b128 v[32:35], v2 offset:21504
	s_waitcnt lgkmcnt(7)
	v_pk_mul_f32 v[46:47], v[16:17], v[144:145] op_sel_hi:[1,0]
	v_pk_mul_f32 v[50:51], v[16:17], v[40:41] op_sel_hi:[1,0]
	v_pk_fma_f32 v[46:47], v[18:19], v[144:145], v[46:47] op_sel:[0,1,0] op_sel_hi:[1,1,1]
	v_pk_fma_f32 v[50:51], v[18:19], v[40:41], v[50:51] op_sel:[0,1,0] op_sel_hi:[1,1,1]
	v_pk_fma_f32 v[46:47], v[20:21], v[146:147], v[46:47] op_sel_hi:[1,0,1]
	v_pk_fma_f32 v[50:51], v[20:21], v[42:43], v[50:51] op_sel_hi:[1,0,1]
	v_pk_fma_f32 v[46:47], v[22:23], v[146:147], v[46:47] op_sel:[0,1,0] op_sel_hi:[1,1,1]
	v_pk_fma_f32 v[50:51], v[22:23], v[42:43], v[50:51] op_sel:[0,1,0] op_sel_hi:[1,1,1]
	ds_read_b128 v[40:43], v2 offset:1024
	v_pk_mul_f32 v[168:169], v[164:165], v[156:157] op_sel_hi:[1,0]
	v_add_f32_dpp v48, v47, v46 quad_perm:[1,0,3,2] row_mask:0xf bank_mask:0xf bound_ctrl:1
	v_add_f32_dpp v52, v51, v50 quad_perm:[1,0,3,2] row_mask:0xf bank_mask:0xf bound_ctrl:1
	v_pk_mul_f32 v[170:171], v[164:165], v[156:157] op_sel:[0,1] op_sel_hi:[1,1]
	v_add_f32_dpp v48, v48, v48 quad_perm:[2,3,0,1] row_mask:0xf bank_mask:0xf bound_ctrl:1
	ds_write_b32 v0, v52 offset:51200
	v_pk_mul_f32 v[172:173], v[164:165], v[158:159] op_sel_hi:[1,0]
	v_pk_mul_f32 v[174:175], v[164:165], v[158:159] op_sel:[0,1] op_sel_hi:[1,1]
	v_add_f32_dpp v48, v48, v48 row_ror:4 row_mask:0xf bank_mask:0xf bound_ctrl:1
	v_pk_fma_f32 v[168:169], v[16:17], v[148:149], v[168:169] op_sel_hi:[1,0,1]
	v_pk_fma_f32 v[170:171], v[18:19], v[148:149], v[170:171] op_sel:[0,1,0] op_sel_hi:[1,1,1]
	v_add_f32_dpp v48, v48, v48 row_ror:8 row_mask:0xf bank_mask:0xf bound_ctrl:1
	v_pk_fma_f32 v[172:173], v[20:21], v[150:151], v[172:173] op_sel_hi:[1,0,1]
	v_pk_fma_f32 v[174:175], v[22:23], v[150:151], v[174:175] op_sel:[0,1,0] op_sel_hi:[1,1,1]
	v_mov_b32_dpp v49, v48 quad_perm:[1,0,3,2] row_mask:0xf bank_mask:0xf bound_ctrl:1
	v_pk_fma_f32 v[16:17], v[48:49], v[152:153], v[168:169] op_sel_hi:[1,0,1] neg_lo:[0,1,0] neg_hi:[0,1,0]
	v_pk_fma_f32 v[18:19], v[48:49], v[152:153], v[170:171] op_sel:[0,1,0] op_sel_hi:[1,1,1] neg_lo:[0,1,0] neg_hi:[0,1,0]
	v_pk_fma_f32 v[20:21], v[48:49], v[154:155], v[172:173] op_sel_hi:[1,0,1] neg_lo:[0,1,0] neg_hi:[0,1,0]
	v_pk_fma_f32 v[22:23], v[48:49], v[154:155], v[174:175] op_sel:[0,1,0] op_sel_hi:[1,1,1] neg_lo:[0,1,0] neg_hi:[0,1,0]
	ds_read_b128 v[144:147], v2 offset:17664
	ds_read_b32 v164, v3 offset:13568
	ds_read_b32 v165, v53 offset:13568
	ds_read_b128 v[156:159], v2 offset:9472
	ds_read_b128 v[148:151], v2 offset:5376
	ds_read_b128 v[152:155], v2 offset:21760
	s_waitcnt lgkmcnt(7)
	v_pk_mul_f32 v[46:47], v[16:17], v[24:25] op_sel_hi:[1,0]
	v_pk_mul_f32 v[50:51], v[16:17], v[160:161] op_sel_hi:[1,0]
	v_pk_fma_f32 v[46:47], v[18:19], v[24:25], v[46:47] op_sel:[0,1,0] op_sel_hi:[1,1,1]
	v_pk_fma_f32 v[50:51], v[18:19], v[160:161], v[50:51] op_sel:[0,1,0] op_sel_hi:[1,1,1]
	v_pk_fma_f32 v[46:47], v[20:21], v[26:27], v[46:47] op_sel_hi:[1,0,1]
	v_pk_fma_f32 v[50:51], v[20:21], v[162:163], v[50:51] op_sel_hi:[1,0,1]
	v_pk_fma_f32 v[46:47], v[22:23], v[26:27], v[46:47] op_sel:[0,1,0] op_sel_hi:[1,1,1]
	v_pk_fma_f32 v[50:51], v[22:23], v[162:163], v[50:51] op_sel:[0,1,0] op_sel_hi:[1,1,1]
	ds_read_b128 v[160:163], v2 offset:1280
	v_pk_mul_f32 v[168:169], v[44:45], v[36:37] op_sel_hi:[1,0]
	v_add_f32_dpp v48, v47, v46 quad_perm:[1,0,3,2] row_mask:0xf bank_mask:0xf bound_ctrl:1
	v_add_f32_dpp v52, v51, v50 quad_perm:[1,0,3,2] row_mask:0xf bank_mask:0xf bound_ctrl:1
	v_pk_mul_f32 v[170:171], v[44:45], v[36:37] op_sel:[0,1] op_sel_hi:[1,1]
	v_add_f32_dpp v48, v48, v48 quad_perm:[2,3,0,1] row_mask:0xf bank_mask:0xf bound_ctrl:1
	ds_write_b32 v0, v52 offset:52224
	v_pk_mul_f32 v[172:173], v[44:45], v[38:39] op_sel_hi:[1,0]
	v_pk_mul_f32 v[174:175], v[44:45], v[38:39] op_sel:[0,1] op_sel_hi:[1,1]
	v_add_f32_dpp v48, v48, v48 row_ror:4 row_mask:0xf bank_mask:0xf bound_ctrl:1
	v_pk_fma_f32 v[168:169], v[16:17], v[28:29], v[168:169] op_sel_hi:[1,0,1]
	v_pk_fma_f32 v[170:171], v[18:19], v[28:29], v[170:171] op_sel:[0,1,0] op_sel_hi:[1,1,1]
	v_add_f32_dpp v48, v48, v48 row_ror:8 row_mask:0xf bank_mask:0xf bound_ctrl:1
	v_pk_fma_f32 v[172:173], v[20:21], v[30:31], v[172:173] op_sel_hi:[1,0,1]
	v_pk_fma_f32 v[174:175], v[22:23], v[30:31], v[174:175] op_sel:[0,1,0] op_sel_hi:[1,1,1]
	v_mov_b32_dpp v49, v48 quad_perm:[1,0,3,2] row_mask:0xf bank_mask:0xf bound_ctrl:1
	v_pk_fma_f32 v[16:17], v[48:49], v[32:33], v[168:169] op_sel_hi:[1,0,1] neg_lo:[0,1,0] neg_hi:[0,1,0]
	v_pk_fma_f32 v[18:19], v[48:49], v[32:33], v[170:171] op_sel:[0,1,0] op_sel_hi:[1,1,1] neg_lo:[0,1,0] neg_hi:[0,1,0]
	v_pk_fma_f32 v[20:21], v[48:49], v[34:35], v[172:173] op_sel_hi:[1,0,1] neg_lo:[0,1,0] neg_hi:[0,1,0]
	v_pk_fma_f32 v[22:23], v[48:49], v[34:35], v[174:175] op_sel:[0,1,0] op_sel_hi:[1,1,1] neg_lo:[0,1,0] neg_hi:[0,1,0]
	ds_read_b128 v[24:27], v2 offset:17920
	ds_read_b32 v44, v3 offset:13824
	ds_read_b32 v45, v53 offset:13824
	ds_read_b128 v[36:39], v2 offset:9728
	ds_read_b128 v[28:31], v2 offset:5632
	ds_read_b128 v[32:35], v2 offset:22016
	s_waitcnt lgkmcnt(7)
	v_pk_mul_f32 v[46:47], v[16:17], v[144:145] op_sel_hi:[1,0]
	v_pk_mul_f32 v[50:51], v[16:17], v[40:41] op_sel_hi:[1,0]
	v_pk_fma_f32 v[46:47], v[18:19], v[144:145], v[46:47] op_sel:[0,1,0] op_sel_hi:[1,1,1]
	v_pk_fma_f32 v[50:51], v[18:19], v[40:41], v[50:51] op_sel:[0,1,0] op_sel_hi:[1,1,1]
	v_pk_fma_f32 v[46:47], v[20:21], v[146:147], v[46:47] op_sel_hi:[1,0,1]
	v_pk_fma_f32 v[50:51], v[20:21], v[42:43], v[50:51] op_sel_hi:[1,0,1]
	v_pk_fma_f32 v[46:47], v[22:23], v[146:147], v[46:47] op_sel:[0,1,0] op_sel_hi:[1,1,1]
	v_pk_fma_f32 v[50:51], v[22:23], v[42:43], v[50:51] op_sel:[0,1,0] op_sel_hi:[1,1,1]
	ds_read_b128 v[40:43], v2 offset:1536
	v_pk_mul_f32 v[168:169], v[164:165], v[156:157] op_sel_hi:[1,0]
	v_add_f32_dpp v48, v47, v46 quad_perm:[1,0,3,2] row_mask:0xf bank_mask:0xf bound_ctrl:1
	v_add_f32_dpp v52, v51, v50 quad_perm:[1,0,3,2] row_mask:0xf bank_mask:0xf bound_ctrl:1
	v_pk_mul_f32 v[170:171], v[164:165], v[156:157] op_sel:[0,1] op_sel_hi:[1,1]
	v_add_f32_dpp v48, v48, v48 quad_perm:[2,3,0,1] row_mask:0xf bank_mask:0xf bound_ctrl:1
	ds_write_b32 v0, v52 offset:53248
	v_pk_mul_f32 v[172:173], v[164:165], v[158:159] op_sel_hi:[1,0]
	v_pk_mul_f32 v[174:175], v[164:165], v[158:159] op_sel:[0,1] op_sel_hi:[1,1]
	v_add_f32_dpp v48, v48, v48 row_ror:4 row_mask:0xf bank_mask:0xf bound_ctrl:1
	v_pk_fma_f32 v[168:169], v[16:17], v[148:149], v[168:169] op_sel_hi:[1,0,1]
	v_pk_fma_f32 v[170:171], v[18:19], v[148:149], v[170:171] op_sel:[0,1,0] op_sel_hi:[1,1,1]
	v_add_f32_dpp v48, v48, v48 row_ror:8 row_mask:0xf bank_mask:0xf bound_ctrl:1
	v_pk_fma_f32 v[172:173], v[20:21], v[150:151], v[172:173] op_sel_hi:[1,0,1]
	v_pk_fma_f32 v[174:175], v[22:23], v[150:151], v[174:175] op_sel:[0,1,0] op_sel_hi:[1,1,1]
	v_mov_b32_dpp v49, v48 quad_perm:[1,0,3,2] row_mask:0xf bank_mask:0xf bound_ctrl:1
	v_pk_fma_f32 v[16:17], v[48:49], v[152:153], v[168:169] op_sel_hi:[1,0,1] neg_lo:[0,1,0] neg_hi:[0,1,0]
	v_pk_fma_f32 v[18:19], v[48:49], v[152:153], v[170:171] op_sel:[0,1,0] op_sel_hi:[1,1,1] neg_lo:[0,1,0] neg_hi:[0,1,0]
	v_pk_fma_f32 v[20:21], v[48:49], v[154:155], v[172:173] op_sel_hi:[1,0,1] neg_lo:[0,1,0] neg_hi:[0,1,0]
	v_pk_fma_f32 v[22:23], v[48:49], v[154:155], v[174:175] op_sel:[0,1,0] op_sel_hi:[1,1,1] neg_lo:[0,1,0] neg_hi:[0,1,0]
	ds_read_b128 v[144:147], v2 offset:18176
	ds_read_b32 v164, v3 offset:14080
	ds_read_b32 v165, v53 offset:14080
	ds_read_b128 v[156:159], v2 offset:9984
	ds_read_b128 v[148:151], v2 offset:5888
	ds_read_b128 v[152:155], v2 offset:22272
	s_waitcnt lgkmcnt(7)
	v_pk_mul_f32 v[46:47], v[16:17], v[24:25] op_sel_hi:[1,0]
	v_pk_mul_f32 v[50:51], v[16:17], v[160:161] op_sel_hi:[1,0]
	v_pk_fma_f32 v[46:47], v[18:19], v[24:25], v[46:47] op_sel:[0,1,0] op_sel_hi:[1,1,1]
	v_pk_fma_f32 v[50:51], v[18:19], v[160:161], v[50:51] op_sel:[0,1,0] op_sel_hi:[1,1,1]
	v_pk_fma_f32 v[46:47], v[20:21], v[26:27], v[46:47] op_sel_hi:[1,0,1]
	v_pk_fma_f32 v[50:51], v[20:21], v[162:163], v[50:51] op_sel_hi:[1,0,1]
	v_pk_fma_f32 v[46:47], v[22:23], v[26:27], v[46:47] op_sel:[0,1,0] op_sel_hi:[1,1,1]
	v_pk_fma_f32 v[50:51], v[22:23], v[162:163], v[50:51] op_sel:[0,1,0] op_sel_hi:[1,1,1]
	ds_read_b128 v[160:163], v2 offset:1792
	v_pk_mul_f32 v[168:169], v[44:45], v[36:37] op_sel_hi:[1,0]
	v_add_f32_dpp v48, v47, v46 quad_perm:[1,0,3,2] row_mask:0xf bank_mask:0xf bound_ctrl:1
	v_add_f32_dpp v52, v51, v50 quad_perm:[1,0,3,2] row_mask:0xf bank_mask:0xf bound_ctrl:1
	v_pk_mul_f32 v[170:171], v[44:45], v[36:37] op_sel:[0,1] op_sel_hi:[1,1]
	v_add_f32_dpp v48, v48, v48 quad_perm:[2,3,0,1] row_mask:0xf bank_mask:0xf bound_ctrl:1
	ds_write_b32 v0, v52 offset:54272
	v_pk_mul_f32 v[172:173], v[44:45], v[38:39] op_sel_hi:[1,0]
	v_pk_mul_f32 v[174:175], v[44:45], v[38:39] op_sel:[0,1] op_sel_hi:[1,1]
	v_add_f32_dpp v48, v48, v48 row_ror:4 row_mask:0xf bank_mask:0xf bound_ctrl:1
	v_pk_fma_f32 v[168:169], v[16:17], v[28:29], v[168:169] op_sel_hi:[1,0,1]
	v_pk_fma_f32 v[170:171], v[18:19], v[28:29], v[170:171] op_sel:[0,1,0] op_sel_hi:[1,1,1]
	v_add_f32_dpp v48, v48, v48 row_ror:8 row_mask:0xf bank_mask:0xf bound_ctrl:1
	v_pk_fma_f32 v[172:173], v[20:21], v[30:31], v[172:173] op_sel_hi:[1,0,1]
	v_pk_fma_f32 v[174:175], v[22:23], v[30:31], v[174:175] op_sel:[0,1,0] op_sel_hi:[1,1,1]
	v_mov_b32_dpp v49, v48 quad_perm:[1,0,3,2] row_mask:0xf bank_mask:0xf bound_ctrl:1
	v_pk_fma_f32 v[16:17], v[48:49], v[32:33], v[168:169] op_sel_hi:[1,0,1] neg_lo:[0,1,0] neg_hi:[0,1,0]
	v_pk_fma_f32 v[18:19], v[48:49], v[32:33], v[170:171] op_sel:[0,1,0] op_sel_hi:[1,1,1] neg_lo:[0,1,0] neg_hi:[0,1,0]
	v_pk_fma_f32 v[20:21], v[48:49], v[34:35], v[172:173] op_sel_hi:[1,0,1] neg_lo:[0,1,0] neg_hi:[0,1,0]
	v_pk_fma_f32 v[22:23], v[48:49], v[34:35], v[174:175] op_sel:[0,1,0] op_sel_hi:[1,1,1] neg_lo:[0,1,0] neg_hi:[0,1,0]
	ds_read_b128 v[24:27], v2 offset:18432
	ds_read_b32 v44, v3 offset:14336
	ds_read_b32 v45, v53 offset:14336
	ds_read_b128 v[36:39], v2 offset:10240
	ds_read_b128 v[28:31], v2 offset:6144
	ds_read_b128 v[32:35], v2 offset:22528
	s_waitcnt lgkmcnt(7)
	v_pk_mul_f32 v[46:47], v[16:17], v[144:145] op_sel_hi:[1,0]
	v_pk_mul_f32 v[50:51], v[16:17], v[40:41] op_sel_hi:[1,0]
	v_pk_fma_f32 v[46:47], v[18:19], v[144:145], v[46:47] op_sel:[0,1,0] op_sel_hi:[1,1,1]
	v_pk_fma_f32 v[50:51], v[18:19], v[40:41], v[50:51] op_sel:[0,1,0] op_sel_hi:[1,1,1]
	v_pk_fma_f32 v[46:47], v[20:21], v[146:147], v[46:47] op_sel_hi:[1,0,1]
	v_pk_fma_f32 v[50:51], v[20:21], v[42:43], v[50:51] op_sel_hi:[1,0,1]
	v_pk_fma_f32 v[46:47], v[22:23], v[146:147], v[46:47] op_sel:[0,1,0] op_sel_hi:[1,1,1]
	v_pk_fma_f32 v[50:51], v[22:23], v[42:43], v[50:51] op_sel:[0,1,0] op_sel_hi:[1,1,1]
	ds_read_b128 v[40:43], v2 offset:2048
	v_pk_mul_f32 v[168:169], v[164:165], v[156:157] op_sel_hi:[1,0]
	v_add_f32_dpp v48, v47, v46 quad_perm:[1,0,3,2] row_mask:0xf bank_mask:0xf bound_ctrl:1
	v_add_f32_dpp v52, v51, v50 quad_perm:[1,0,3,2] row_mask:0xf bank_mask:0xf bound_ctrl:1
	v_pk_mul_f32 v[170:171], v[164:165], v[156:157] op_sel:[0,1] op_sel_hi:[1,1]
	v_add_f32_dpp v48, v48, v48 quad_perm:[2,3,0,1] row_mask:0xf bank_mask:0xf bound_ctrl:1
	ds_write_b32 v0, v52 offset:55296
	v_pk_mul_f32 v[172:173], v[164:165], v[158:159] op_sel_hi:[1,0]
	v_pk_mul_f32 v[174:175], v[164:165], v[158:159] op_sel:[0,1] op_sel_hi:[1,1]
	v_add_f32_dpp v48, v48, v48 row_ror:4 row_mask:0xf bank_mask:0xf bound_ctrl:1
	v_pk_fma_f32 v[168:169], v[16:17], v[148:149], v[168:169] op_sel_hi:[1,0,1]
	v_pk_fma_f32 v[170:171], v[18:19], v[148:149], v[170:171] op_sel:[0,1,0] op_sel_hi:[1,1,1]
	v_add_f32_dpp v48, v48, v48 row_ror:8 row_mask:0xf bank_mask:0xf bound_ctrl:1
	v_pk_fma_f32 v[172:173], v[20:21], v[150:151], v[172:173] op_sel_hi:[1,0,1]
	v_pk_fma_f32 v[174:175], v[22:23], v[150:151], v[174:175] op_sel:[0,1,0] op_sel_hi:[1,1,1]
	v_mov_b32_dpp v49, v48 quad_perm:[1,0,3,2] row_mask:0xf bank_mask:0xf bound_ctrl:1
	v_pk_fma_f32 v[16:17], v[48:49], v[152:153], v[168:169] op_sel_hi:[1,0,1] neg_lo:[0,1,0] neg_hi:[0,1,0]
	v_pk_fma_f32 v[18:19], v[48:49], v[152:153], v[170:171] op_sel:[0,1,0] op_sel_hi:[1,1,1] neg_lo:[0,1,0] neg_hi:[0,1,0]
	v_pk_fma_f32 v[20:21], v[48:49], v[154:155], v[172:173] op_sel_hi:[1,0,1] neg_lo:[0,1,0] neg_hi:[0,1,0]
	v_pk_fma_f32 v[22:23], v[48:49], v[154:155], v[174:175] op_sel:[0,1,0] op_sel_hi:[1,1,1] neg_lo:[0,1,0] neg_hi:[0,1,0]
	ds_read_b128 v[144:147], v2 offset:18688
	ds_read_b32 v164, v3 offset:14592
	ds_read_b32 v165, v53 offset:14592
	ds_read_b128 v[156:159], v2 offset:10496
	ds_read_b128 v[148:151], v2 offset:6400
	ds_read_b128 v[152:155], v2 offset:22784
	s_waitcnt lgkmcnt(7)
	v_pk_mul_f32 v[46:47], v[16:17], v[24:25] op_sel_hi:[1,0]
	v_pk_mul_f32 v[50:51], v[16:17], v[160:161] op_sel_hi:[1,0]
	v_pk_fma_f32 v[46:47], v[18:19], v[24:25], v[46:47] op_sel:[0,1,0] op_sel_hi:[1,1,1]
	v_pk_fma_f32 v[50:51], v[18:19], v[160:161], v[50:51] op_sel:[0,1,0] op_sel_hi:[1,1,1]
	v_pk_fma_f32 v[46:47], v[20:21], v[26:27], v[46:47] op_sel_hi:[1,0,1]
	v_pk_fma_f32 v[50:51], v[20:21], v[162:163], v[50:51] op_sel_hi:[1,0,1]
	v_pk_fma_f32 v[46:47], v[22:23], v[26:27], v[46:47] op_sel:[0,1,0] op_sel_hi:[1,1,1]
	v_pk_fma_f32 v[50:51], v[22:23], v[162:163], v[50:51] op_sel:[0,1,0] op_sel_hi:[1,1,1]
	ds_read_b128 v[160:163], v2 offset:2304
	v_pk_mul_f32 v[168:169], v[44:45], v[36:37] op_sel_hi:[1,0]
	v_add_f32_dpp v48, v47, v46 quad_perm:[1,0,3,2] row_mask:0xf bank_mask:0xf bound_ctrl:1
	v_add_f32_dpp v52, v51, v50 quad_perm:[1,0,3,2] row_mask:0xf bank_mask:0xf bound_ctrl:1
	v_pk_mul_f32 v[170:171], v[44:45], v[36:37] op_sel:[0,1] op_sel_hi:[1,1]
	v_add_f32_dpp v48, v48, v48 quad_perm:[2,3,0,1] row_mask:0xf bank_mask:0xf bound_ctrl:1
	ds_write_b32 v0, v52 offset:56320
	v_pk_mul_f32 v[172:173], v[44:45], v[38:39] op_sel_hi:[1,0]
	v_pk_mul_f32 v[174:175], v[44:45], v[38:39] op_sel:[0,1] op_sel_hi:[1,1]
	v_add_f32_dpp v48, v48, v48 row_ror:4 row_mask:0xf bank_mask:0xf bound_ctrl:1
	v_pk_fma_f32 v[168:169], v[16:17], v[28:29], v[168:169] op_sel_hi:[1,0,1]
	v_pk_fma_f32 v[170:171], v[18:19], v[28:29], v[170:171] op_sel:[0,1,0] op_sel_hi:[1,1,1]
	v_add_f32_dpp v48, v48, v48 row_ror:8 row_mask:0xf bank_mask:0xf bound_ctrl:1
	v_pk_fma_f32 v[172:173], v[20:21], v[30:31], v[172:173] op_sel_hi:[1,0,1]
	v_pk_fma_f32 v[174:175], v[22:23], v[30:31], v[174:175] op_sel:[0,1,0] op_sel_hi:[1,1,1]
	v_mov_b32_dpp v49, v48 quad_perm:[1,0,3,2] row_mask:0xf bank_mask:0xf bound_ctrl:1
	v_pk_fma_f32 v[16:17], v[48:49], v[32:33], v[168:169] op_sel_hi:[1,0,1] neg_lo:[0,1,0] neg_hi:[0,1,0]
	v_pk_fma_f32 v[18:19], v[48:49], v[32:33], v[170:171] op_sel:[0,1,0] op_sel_hi:[1,1,1] neg_lo:[0,1,0] neg_hi:[0,1,0]
	v_pk_fma_f32 v[20:21], v[48:49], v[34:35], v[172:173] op_sel_hi:[1,0,1] neg_lo:[0,1,0] neg_hi:[0,1,0]
	v_pk_fma_f32 v[22:23], v[48:49], v[34:35], v[174:175] op_sel:[0,1,0] op_sel_hi:[1,1,1] neg_lo:[0,1,0] neg_hi:[0,1,0]
	ds_read_b128 v[24:27], v2 offset:18944
	ds_read_b32 v44, v3 offset:14848
	ds_read_b32 v45, v53 offset:14848
	ds_read_b128 v[36:39], v2 offset:10752
	ds_read_b128 v[28:31], v2 offset:6656
	ds_read_b128 v[32:35], v2 offset:23040
	s_waitcnt lgkmcnt(7)
	v_pk_mul_f32 v[46:47], v[16:17], v[144:145] op_sel_hi:[1,0]
	v_pk_mul_f32 v[50:51], v[16:17], v[40:41] op_sel_hi:[1,0]
	v_pk_fma_f32 v[46:47], v[18:19], v[144:145], v[46:47] op_sel:[0,1,0] op_sel_hi:[1,1,1]
	v_pk_fma_f32 v[50:51], v[18:19], v[40:41], v[50:51] op_sel:[0,1,0] op_sel_hi:[1,1,1]
	v_pk_fma_f32 v[46:47], v[20:21], v[146:147], v[46:47] op_sel_hi:[1,0,1]
	v_pk_fma_f32 v[50:51], v[20:21], v[42:43], v[50:51] op_sel_hi:[1,0,1]
	v_pk_fma_f32 v[46:47], v[22:23], v[146:147], v[46:47] op_sel:[0,1,0] op_sel_hi:[1,1,1]
	v_pk_fma_f32 v[50:51], v[22:23], v[42:43], v[50:51] op_sel:[0,1,0] op_sel_hi:[1,1,1]
	ds_read_b128 v[40:43], v2 offset:2560
	v_pk_mul_f32 v[168:169], v[164:165], v[156:157] op_sel_hi:[1,0]
	v_add_f32_dpp v48, v47, v46 quad_perm:[1,0,3,2] row_mask:0xf bank_mask:0xf bound_ctrl:1
	v_add_f32_dpp v52, v51, v50 quad_perm:[1,0,3,2] row_mask:0xf bank_mask:0xf bound_ctrl:1
	v_pk_mul_f32 v[170:171], v[164:165], v[156:157] op_sel:[0,1] op_sel_hi:[1,1]
	v_add_f32_dpp v48, v48, v48 quad_perm:[2,3,0,1] row_mask:0xf bank_mask:0xf bound_ctrl:1
	ds_write_b32 v0, v52 offset:57344
	v_pk_mul_f32 v[172:173], v[164:165], v[158:159] op_sel_hi:[1,0]
	v_pk_mul_f32 v[174:175], v[164:165], v[158:159] op_sel:[0,1] op_sel_hi:[1,1]
	v_add_f32_dpp v48, v48, v48 row_ror:4 row_mask:0xf bank_mask:0xf bound_ctrl:1
	v_pk_fma_f32 v[168:169], v[16:17], v[148:149], v[168:169] op_sel_hi:[1,0,1]
	v_pk_fma_f32 v[170:171], v[18:19], v[148:149], v[170:171] op_sel:[0,1,0] op_sel_hi:[1,1,1]
	v_add_f32_dpp v48, v48, v48 row_ror:8 row_mask:0xf bank_mask:0xf bound_ctrl:1
	v_pk_fma_f32 v[172:173], v[20:21], v[150:151], v[172:173] op_sel_hi:[1,0,1]
	v_pk_fma_f32 v[174:175], v[22:23], v[150:151], v[174:175] op_sel:[0,1,0] op_sel_hi:[1,1,1]
	v_mov_b32_dpp v49, v48 quad_perm:[1,0,3,2] row_mask:0xf bank_mask:0xf bound_ctrl:1
	v_pk_fma_f32 v[16:17], v[48:49], v[152:153], v[168:169] op_sel_hi:[1,0,1] neg_lo:[0,1,0] neg_hi:[0,1,0]
	v_pk_fma_f32 v[18:19], v[48:49], v[152:153], v[170:171] op_sel:[0,1,0] op_sel_hi:[1,1,1] neg_lo:[0,1,0] neg_hi:[0,1,0]
	v_pk_fma_f32 v[20:21], v[48:49], v[154:155], v[172:173] op_sel_hi:[1,0,1] neg_lo:[0,1,0] neg_hi:[0,1,0]
	v_pk_fma_f32 v[22:23], v[48:49], v[154:155], v[174:175] op_sel:[0,1,0] op_sel_hi:[1,1,1] neg_lo:[0,1,0] neg_hi:[0,1,0]
	ds_read_b128 v[144:147], v2 offset:19200
	ds_read_b32 v164, v3 offset:15104
	ds_read_b32 v165, v53 offset:15104
	ds_read_b128 v[156:159], v2 offset:11008
	ds_read_b128 v[148:151], v2 offset:6912
	ds_read_b128 v[152:155], v2 offset:23296
	s_waitcnt lgkmcnt(7)
	v_pk_mul_f32 v[46:47], v[16:17], v[24:25] op_sel_hi:[1,0]
	v_pk_mul_f32 v[50:51], v[16:17], v[160:161] op_sel_hi:[1,0]
	v_pk_fma_f32 v[46:47], v[18:19], v[24:25], v[46:47] op_sel:[0,1,0] op_sel_hi:[1,1,1]
	v_pk_fma_f32 v[50:51], v[18:19], v[160:161], v[50:51] op_sel:[0,1,0] op_sel_hi:[1,1,1]
	v_pk_fma_f32 v[46:47], v[20:21], v[26:27], v[46:47] op_sel_hi:[1,0,1]
	v_pk_fma_f32 v[50:51], v[20:21], v[162:163], v[50:51] op_sel_hi:[1,0,1]
	v_pk_fma_f32 v[46:47], v[22:23], v[26:27], v[46:47] op_sel:[0,1,0] op_sel_hi:[1,1,1]
	v_pk_fma_f32 v[50:51], v[22:23], v[162:163], v[50:51] op_sel:[0,1,0] op_sel_hi:[1,1,1]
	ds_read_b128 v[160:163], v2 offset:2816
	v_pk_mul_f32 v[168:169], v[44:45], v[36:37] op_sel_hi:[1,0]
	v_add_f32_dpp v48, v47, v46 quad_perm:[1,0,3,2] row_mask:0xf bank_mask:0xf bound_ctrl:1
	v_add_f32_dpp v52, v51, v50 quad_perm:[1,0,3,2] row_mask:0xf bank_mask:0xf bound_ctrl:1
	v_pk_mul_f32 v[170:171], v[44:45], v[36:37] op_sel:[0,1] op_sel_hi:[1,1]
	v_add_f32_dpp v48, v48, v48 quad_perm:[2,3,0,1] row_mask:0xf bank_mask:0xf bound_ctrl:1
	ds_write_b32 v0, v52 offset:58368
	v_pk_mul_f32 v[172:173], v[44:45], v[38:39] op_sel_hi:[1,0]
	v_pk_mul_f32 v[174:175], v[44:45], v[38:39] op_sel:[0,1] op_sel_hi:[1,1]
	v_add_f32_dpp v48, v48, v48 row_ror:4 row_mask:0xf bank_mask:0xf bound_ctrl:1
	v_pk_fma_f32 v[168:169], v[16:17], v[28:29], v[168:169] op_sel_hi:[1,0,1]
	v_pk_fma_f32 v[170:171], v[18:19], v[28:29], v[170:171] op_sel:[0,1,0] op_sel_hi:[1,1,1]
	v_add_f32_dpp v48, v48, v48 row_ror:8 row_mask:0xf bank_mask:0xf bound_ctrl:1
	v_pk_fma_f32 v[172:173], v[20:21], v[30:31], v[172:173] op_sel_hi:[1,0,1]
	v_pk_fma_f32 v[174:175], v[22:23], v[30:31], v[174:175] op_sel:[0,1,0] op_sel_hi:[1,1,1]
	v_mov_b32_dpp v49, v48 quad_perm:[1,0,3,2] row_mask:0xf bank_mask:0xf bound_ctrl:1
	v_pk_fma_f32 v[16:17], v[48:49], v[32:33], v[168:169] op_sel_hi:[1,0,1] neg_lo:[0,1,0] neg_hi:[0,1,0]
	v_pk_fma_f32 v[18:19], v[48:49], v[32:33], v[170:171] op_sel:[0,1,0] op_sel_hi:[1,1,1] neg_lo:[0,1,0] neg_hi:[0,1,0]
	v_pk_fma_f32 v[20:21], v[48:49], v[34:35], v[172:173] op_sel_hi:[1,0,1] neg_lo:[0,1,0] neg_hi:[0,1,0]
	v_pk_fma_f32 v[22:23], v[48:49], v[34:35], v[174:175] op_sel:[0,1,0] op_sel_hi:[1,1,1] neg_lo:[0,1,0] neg_hi:[0,1,0]
	ds_read_b128 v[24:27], v2 offset:19456
	ds_read_b32 v44, v3 offset:15360
	ds_read_b32 v45, v53 offset:15360
	ds_read_b128 v[36:39], v2 offset:11264
	ds_read_b128 v[28:31], v2 offset:7168
	ds_read_b128 v[32:35], v2 offset:23552
	s_waitcnt lgkmcnt(7)
	v_pk_mul_f32 v[46:47], v[16:17], v[144:145] op_sel_hi:[1,0]
	v_pk_mul_f32 v[50:51], v[16:17], v[40:41] op_sel_hi:[1,0]
	v_pk_fma_f32 v[46:47], v[18:19], v[144:145], v[46:47] op_sel:[0,1,0] op_sel_hi:[1,1,1]
	v_pk_fma_f32 v[50:51], v[18:19], v[40:41], v[50:51] op_sel:[0,1,0] op_sel_hi:[1,1,1]
	v_pk_fma_f32 v[46:47], v[20:21], v[146:147], v[46:47] op_sel_hi:[1,0,1]
	v_pk_fma_f32 v[50:51], v[20:21], v[42:43], v[50:51] op_sel_hi:[1,0,1]
	v_pk_fma_f32 v[46:47], v[22:23], v[146:147], v[46:47] op_sel:[0,1,0] op_sel_hi:[1,1,1]
	v_pk_fma_f32 v[50:51], v[22:23], v[42:43], v[50:51] op_sel:[0,1,0] op_sel_hi:[1,1,1]
	ds_read_b128 v[40:43], v2 offset:3072
	v_pk_mul_f32 v[168:169], v[164:165], v[156:157] op_sel_hi:[1,0]
	v_add_f32_dpp v48, v47, v46 quad_perm:[1,0,3,2] row_mask:0xf bank_mask:0xf bound_ctrl:1
	v_add_f32_dpp v52, v51, v50 quad_perm:[1,0,3,2] row_mask:0xf bank_mask:0xf bound_ctrl:1
	v_pk_mul_f32 v[170:171], v[164:165], v[156:157] op_sel:[0,1] op_sel_hi:[1,1]
	v_add_f32_dpp v48, v48, v48 quad_perm:[2,3,0,1] row_mask:0xf bank_mask:0xf bound_ctrl:1
	ds_write_b32 v0, v52 offset:59392
	v_pk_mul_f32 v[172:173], v[164:165], v[158:159] op_sel_hi:[1,0]
	v_pk_mul_f32 v[174:175], v[164:165], v[158:159] op_sel:[0,1] op_sel_hi:[1,1]
	v_add_f32_dpp v48, v48, v48 row_ror:4 row_mask:0xf bank_mask:0xf bound_ctrl:1
	v_pk_fma_f32 v[168:169], v[16:17], v[148:149], v[168:169] op_sel_hi:[1,0,1]
	v_pk_fma_f32 v[170:171], v[18:19], v[148:149], v[170:171] op_sel:[0,1,0] op_sel_hi:[1,1,1]
	v_add_f32_dpp v48, v48, v48 row_ror:8 row_mask:0xf bank_mask:0xf bound_ctrl:1
	v_pk_fma_f32 v[172:173], v[20:21], v[150:151], v[172:173] op_sel_hi:[1,0,1]
	v_pk_fma_f32 v[174:175], v[22:23], v[150:151], v[174:175] op_sel:[0,1,0] op_sel_hi:[1,1,1]
	v_mov_b32_dpp v49, v48 quad_perm:[1,0,3,2] row_mask:0xf bank_mask:0xf bound_ctrl:1
	v_pk_fma_f32 v[16:17], v[48:49], v[152:153], v[168:169] op_sel_hi:[1,0,1] neg_lo:[0,1,0] neg_hi:[0,1,0]
	v_pk_fma_f32 v[18:19], v[48:49], v[152:153], v[170:171] op_sel:[0,1,0] op_sel_hi:[1,1,1] neg_lo:[0,1,0] neg_hi:[0,1,0]
	v_pk_fma_f32 v[20:21], v[48:49], v[154:155], v[172:173] op_sel_hi:[1,0,1] neg_lo:[0,1,0] neg_hi:[0,1,0]
	v_pk_fma_f32 v[22:23], v[48:49], v[154:155], v[174:175] op_sel:[0,1,0] op_sel_hi:[1,1,1] neg_lo:[0,1,0] neg_hi:[0,1,0]
	ds_read_b128 v[144:147], v2 offset:19712
	ds_read_b32 v164, v3 offset:15616
	ds_read_b32 v165, v53 offset:15616
	ds_read_b128 v[156:159], v2 offset:11520
	ds_read_b128 v[148:151], v2 offset:7424
	ds_read_b128 v[152:155], v2 offset:23808
	s_waitcnt lgkmcnt(7)
	v_pk_mul_f32 v[46:47], v[16:17], v[24:25] op_sel_hi:[1,0]
	v_pk_mul_f32 v[50:51], v[16:17], v[160:161] op_sel_hi:[1,0]
	v_pk_fma_f32 v[46:47], v[18:19], v[24:25], v[46:47] op_sel:[0,1,0] op_sel_hi:[1,1,1]
	v_pk_fma_f32 v[50:51], v[18:19], v[160:161], v[50:51] op_sel:[0,1,0] op_sel_hi:[1,1,1]
	v_pk_fma_f32 v[46:47], v[20:21], v[26:27], v[46:47] op_sel_hi:[1,0,1]
	v_pk_fma_f32 v[50:51], v[20:21], v[162:163], v[50:51] op_sel_hi:[1,0,1]
	v_pk_fma_f32 v[46:47], v[22:23], v[26:27], v[46:47] op_sel:[0,1,0] op_sel_hi:[1,1,1]
	v_pk_fma_f32 v[50:51], v[22:23], v[162:163], v[50:51] op_sel:[0,1,0] op_sel_hi:[1,1,1]
	ds_read_b128 v[160:163], v2 offset:3328
	v_pk_mul_f32 v[168:169], v[44:45], v[36:37] op_sel_hi:[1,0]
	v_add_f32_dpp v48, v47, v46 quad_perm:[1,0,3,2] row_mask:0xf bank_mask:0xf bound_ctrl:1
	v_add_f32_dpp v52, v51, v50 quad_perm:[1,0,3,2] row_mask:0xf bank_mask:0xf bound_ctrl:1
	v_pk_mul_f32 v[170:171], v[44:45], v[36:37] op_sel:[0,1] op_sel_hi:[1,1]
	v_add_f32_dpp v48, v48, v48 quad_perm:[2,3,0,1] row_mask:0xf bank_mask:0xf bound_ctrl:1
	ds_write_b32 v0, v52 offset:60416
	v_pk_mul_f32 v[172:173], v[44:45], v[38:39] op_sel_hi:[1,0]
	v_pk_mul_f32 v[174:175], v[44:45], v[38:39] op_sel:[0,1] op_sel_hi:[1,1]
	v_add_f32_dpp v48, v48, v48 row_ror:4 row_mask:0xf bank_mask:0xf bound_ctrl:1
	v_pk_fma_f32 v[168:169], v[16:17], v[28:29], v[168:169] op_sel_hi:[1,0,1]
	v_pk_fma_f32 v[170:171], v[18:19], v[28:29], v[170:171] op_sel:[0,1,0] op_sel_hi:[1,1,1]
	v_add_f32_dpp v48, v48, v48 row_ror:8 row_mask:0xf bank_mask:0xf bound_ctrl:1
	v_pk_fma_f32 v[172:173], v[20:21], v[30:31], v[172:173] op_sel_hi:[1,0,1]
	v_pk_fma_f32 v[174:175], v[22:23], v[30:31], v[174:175] op_sel:[0,1,0] op_sel_hi:[1,1,1]
	v_mov_b32_dpp v49, v48 quad_perm:[1,0,3,2] row_mask:0xf bank_mask:0xf bound_ctrl:1
	v_pk_fma_f32 v[16:17], v[48:49], v[32:33], v[168:169] op_sel_hi:[1,0,1] neg_lo:[0,1,0] neg_hi:[0,1,0]
	v_pk_fma_f32 v[18:19], v[48:49], v[32:33], v[170:171] op_sel:[0,1,0] op_sel_hi:[1,1,1] neg_lo:[0,1,0] neg_hi:[0,1,0]
	v_pk_fma_f32 v[20:21], v[48:49], v[34:35], v[172:173] op_sel_hi:[1,0,1] neg_lo:[0,1,0] neg_hi:[0,1,0]
	v_pk_fma_f32 v[22:23], v[48:49], v[34:35], v[174:175] op_sel:[0,1,0] op_sel_hi:[1,1,1] neg_lo:[0,1,0] neg_hi:[0,1,0]
	ds_read_b128 v[24:27], v2 offset:19968
	ds_read_b32 v44, v3 offset:15872
	ds_read_b32 v45, v53 offset:15872
	ds_read_b128 v[36:39], v2 offset:11776
	ds_read_b128 v[28:31], v2 offset:7680
	ds_read_b128 v[32:35], v2 offset:24064
	s_waitcnt lgkmcnt(7)
	v_pk_mul_f32 v[46:47], v[16:17], v[144:145] op_sel_hi:[1,0]
	v_pk_mul_f32 v[50:51], v[16:17], v[40:41] op_sel_hi:[1,0]
	v_pk_fma_f32 v[46:47], v[18:19], v[144:145], v[46:47] op_sel:[0,1,0] op_sel_hi:[1,1,1]
	v_pk_fma_f32 v[50:51], v[18:19], v[40:41], v[50:51] op_sel:[0,1,0] op_sel_hi:[1,1,1]
	v_pk_fma_f32 v[46:47], v[20:21], v[146:147], v[46:47] op_sel_hi:[1,0,1]
	v_pk_fma_f32 v[50:51], v[20:21], v[42:43], v[50:51] op_sel_hi:[1,0,1]
	v_pk_fma_f32 v[46:47], v[22:23], v[146:147], v[46:47] op_sel:[0,1,0] op_sel_hi:[1,1,1]
	v_pk_fma_f32 v[50:51], v[22:23], v[42:43], v[50:51] op_sel:[0,1,0] op_sel_hi:[1,1,1]
	ds_read_b128 v[40:43], v2 offset:3584
	v_pk_mul_f32 v[168:169], v[164:165], v[156:157] op_sel_hi:[1,0]
	v_add_f32_dpp v48, v47, v46 quad_perm:[1,0,3,2] row_mask:0xf bank_mask:0xf bound_ctrl:1
	v_add_f32_dpp v52, v51, v50 quad_perm:[1,0,3,2] row_mask:0xf bank_mask:0xf bound_ctrl:1
	v_pk_mul_f32 v[170:171], v[164:165], v[156:157] op_sel:[0,1] op_sel_hi:[1,1]
	v_add_f32_dpp v48, v48, v48 quad_perm:[2,3,0,1] row_mask:0xf bank_mask:0xf bound_ctrl:1
	ds_write_b32 v0, v52 offset:61440
	v_pk_mul_f32 v[172:173], v[164:165], v[158:159] op_sel_hi:[1,0]
	v_pk_mul_f32 v[174:175], v[164:165], v[158:159] op_sel:[0,1] op_sel_hi:[1,1]
	v_add_f32_dpp v48, v48, v48 row_ror:4 row_mask:0xf bank_mask:0xf bound_ctrl:1
	v_pk_fma_f32 v[168:169], v[16:17], v[148:149], v[168:169] op_sel_hi:[1,0,1]
	v_pk_fma_f32 v[170:171], v[18:19], v[148:149], v[170:171] op_sel:[0,1,0] op_sel_hi:[1,1,1]
	v_add_f32_dpp v48, v48, v48 row_ror:8 row_mask:0xf bank_mask:0xf bound_ctrl:1
	v_pk_fma_f32 v[172:173], v[20:21], v[150:151], v[172:173] op_sel_hi:[1,0,1]
	v_pk_fma_f32 v[174:175], v[22:23], v[150:151], v[174:175] op_sel:[0,1,0] op_sel_hi:[1,1,1]
	v_mov_b32_dpp v49, v48 quad_perm:[1,0,3,2] row_mask:0xf bank_mask:0xf bound_ctrl:1
	v_pk_fma_f32 v[16:17], v[48:49], v[152:153], v[168:169] op_sel_hi:[1,0,1] neg_lo:[0,1,0] neg_hi:[0,1,0]
	v_pk_fma_f32 v[18:19], v[48:49], v[152:153], v[170:171] op_sel:[0,1,0] op_sel_hi:[1,1,1] neg_lo:[0,1,0] neg_hi:[0,1,0]
	v_pk_fma_f32 v[20:21], v[48:49], v[154:155], v[172:173] op_sel_hi:[1,0,1] neg_lo:[0,1,0] neg_hi:[0,1,0]
	v_pk_fma_f32 v[22:23], v[48:49], v[154:155], v[174:175] op_sel:[0,1,0] op_sel_hi:[1,1,1] neg_lo:[0,1,0] neg_hi:[0,1,0]
	ds_read_b128 v[144:147], v2 offset:20224
	ds_read_b32 v164, v3 offset:16128
	ds_read_b32 v165, v53 offset:16128
	ds_read_b128 v[156:159], v2 offset:12032
	ds_read_b128 v[148:151], v2 offset:7936
	ds_read_b128 v[152:155], v2 offset:24320
	s_waitcnt lgkmcnt(7)
	v_pk_mul_f32 v[46:47], v[16:17], v[24:25] op_sel_hi:[1,0]
	v_pk_mul_f32 v[50:51], v[16:17], v[160:161] op_sel_hi:[1,0]
	v_pk_fma_f32 v[46:47], v[18:19], v[24:25], v[46:47] op_sel:[0,1,0] op_sel_hi:[1,1,1]
	v_pk_fma_f32 v[50:51], v[18:19], v[160:161], v[50:51] op_sel:[0,1,0] op_sel_hi:[1,1,1]
	v_pk_fma_f32 v[46:47], v[20:21], v[26:27], v[46:47] op_sel_hi:[1,0,1]
	v_pk_fma_f32 v[50:51], v[20:21], v[162:163], v[50:51] op_sel_hi:[1,0,1]
	v_pk_fma_f32 v[46:47], v[22:23], v[26:27], v[46:47] op_sel:[0,1,0] op_sel_hi:[1,1,1]
	v_pk_fma_f32 v[50:51], v[22:23], v[162:163], v[50:51] op_sel:[0,1,0] op_sel_hi:[1,1,1]
	ds_read_b128 v[160:163], v2 offset:3840
	v_pk_mul_f32 v[168:169], v[44:45], v[36:37] op_sel_hi:[1,0]
	v_add_f32_dpp v48, v47, v46 quad_perm:[1,0,3,2] row_mask:0xf bank_mask:0xf bound_ctrl:1
	v_add_f32_dpp v52, v51, v50 quad_perm:[1,0,3,2] row_mask:0xf bank_mask:0xf bound_ctrl:1
	v_pk_mul_f32 v[170:171], v[44:45], v[36:37] op_sel:[0,1] op_sel_hi:[1,1]
	v_add_f32_dpp v48, v48, v48 quad_perm:[2,3,0,1] row_mask:0xf bank_mask:0xf bound_ctrl:1
	ds_write_b32 v0, v52 offset:62464
	v_pk_mul_f32 v[172:173], v[44:45], v[38:39] op_sel_hi:[1,0]
	v_pk_mul_f32 v[174:175], v[44:45], v[38:39] op_sel:[0,1] op_sel_hi:[1,1]
	v_add_f32_dpp v48, v48, v48 row_ror:4 row_mask:0xf bank_mask:0xf bound_ctrl:1
	v_pk_fma_f32 v[168:169], v[16:17], v[28:29], v[168:169] op_sel_hi:[1,0,1]
	v_pk_fma_f32 v[170:171], v[18:19], v[28:29], v[170:171] op_sel:[0,1,0] op_sel_hi:[1,1,1]
	v_add_f32_dpp v48, v48, v48 row_ror:8 row_mask:0xf bank_mask:0xf bound_ctrl:1
	v_pk_fma_f32 v[172:173], v[20:21], v[30:31], v[172:173] op_sel_hi:[1,0,1]
	v_pk_fma_f32 v[174:175], v[22:23], v[30:31], v[174:175] op_sel:[0,1,0] op_sel_hi:[1,1,1]
	v_mov_b32_dpp v49, v48 quad_perm:[1,0,3,2] row_mask:0xf bank_mask:0xf bound_ctrl:1
	v_pk_fma_f32 v[16:17], v[48:49], v[32:33], v[168:169] op_sel_hi:[1,0,1] neg_lo:[0,1,0] neg_hi:[0,1,0]
	v_pk_fma_f32 v[18:19], v[48:49], v[32:33], v[170:171] op_sel:[0,1,0] op_sel_hi:[1,1,1] neg_lo:[0,1,0] neg_hi:[0,1,0]
	v_pk_fma_f32 v[20:21], v[48:49], v[34:35], v[172:173] op_sel_hi:[1,0,1] neg_lo:[0,1,0] neg_hi:[0,1,0]
	v_pk_fma_f32 v[22:23], v[48:49], v[34:35], v[174:175] op_sel:[0,1,0] op_sel_hi:[1,1,1] neg_lo:[0,1,0] neg_hi:[0,1,0]
	s_waitcnt lgkmcnt(1)
	v_pk_mul_f32 v[46:47], v[16:17], v[144:145] op_sel_hi:[1,0]
	v_pk_mul_f32 v[50:51], v[16:17], v[40:41] op_sel_hi:[1,0]
	v_pk_fma_f32 v[46:47], v[18:19], v[144:145], v[46:47] op_sel:[0,1,0] op_sel_hi:[1,1,1]
	v_pk_fma_f32 v[50:51], v[18:19], v[40:41], v[50:51] op_sel:[0,1,0] op_sel_hi:[1,1,1]
	v_pk_fma_f32 v[46:47], v[20:21], v[146:147], v[46:47] op_sel_hi:[1,0,1]
	v_pk_fma_f32 v[50:51], v[20:21], v[42:43], v[50:51] op_sel_hi:[1,0,1]
	v_pk_fma_f32 v[46:47], v[22:23], v[146:147], v[46:47] op_sel:[0,1,0] op_sel_hi:[1,1,1]
	v_pk_fma_f32 v[50:51], v[22:23], v[42:43], v[50:51] op_sel:[0,1,0] op_sel_hi:[1,1,1]
	v_pk_mul_f32 v[168:169], v[164:165], v[156:157] op_sel_hi:[1,0]
	v_add_f32_dpp v48, v47, v46 quad_perm:[1,0,3,2] row_mask:0xf bank_mask:0xf bound_ctrl:1
	v_add_f32_dpp v52, v51, v50 quad_perm:[1,0,3,2] row_mask:0xf bank_mask:0xf bound_ctrl:1
	v_pk_mul_f32 v[170:171], v[164:165], v[156:157] op_sel:[0,1] op_sel_hi:[1,1]
	v_add_f32_dpp v48, v48, v48 quad_perm:[2,3,0,1] row_mask:0xf bank_mask:0xf bound_ctrl:1
	ds_write_b32 v0, v52 offset:63488
	v_pk_mul_f32 v[172:173], v[164:165], v[158:159] op_sel_hi:[1,0]
	v_pk_mul_f32 v[174:175], v[164:165], v[158:159] op_sel:[0,1] op_sel_hi:[1,1]
	v_add_f32_dpp v48, v48, v48 row_ror:4 row_mask:0xf bank_mask:0xf bound_ctrl:1
	v_pk_fma_f32 v[168:169], v[16:17], v[148:149], v[168:169] op_sel_hi:[1,0,1]
	v_pk_fma_f32 v[170:171], v[18:19], v[148:149], v[170:171] op_sel:[0,1,0] op_sel_hi:[1,1,1]
	v_add_f32_dpp v48, v48, v48 row_ror:8 row_mask:0xf bank_mask:0xf bound_ctrl:1
	v_pk_fma_f32 v[172:173], v[20:21], v[150:151], v[172:173] op_sel_hi:[1,0,1]
	v_pk_fma_f32 v[174:175], v[22:23], v[150:151], v[174:175] op_sel:[0,1,0] op_sel_hi:[1,1,1]
	v_mov_b32_dpp v49, v48 quad_perm:[1,0,3,2] row_mask:0xf bank_mask:0xf bound_ctrl:1
	v_pk_fma_f32 v[16:17], v[48:49], v[152:153], v[168:169] op_sel_hi:[1,0,1] neg_lo:[0,1,0] neg_hi:[0,1,0]
	v_pk_fma_f32 v[18:19], v[48:49], v[152:153], v[170:171] op_sel:[0,1,0] op_sel_hi:[1,1,1] neg_lo:[0,1,0] neg_hi:[0,1,0]
	v_pk_fma_f32 v[20:21], v[48:49], v[154:155], v[172:173] op_sel_hi:[1,0,1] neg_lo:[0,1,0] neg_hi:[0,1,0]
	v_pk_fma_f32 v[22:23], v[48:49], v[154:155], v[174:175] op_sel:[0,1,0] op_sel_hi:[1,1,1] neg_lo:[0,1,0] neg_hi:[0,1,0]
	v_pk_mul_f32 v[50:51], v[16:17], v[160:161] op_sel_hi:[1,0]
	v_pk_fma_f32 v[50:51], v[18:19], v[160:161], v[50:51] op_sel:[0,1,0] op_sel_hi:[1,1,1]
	v_pk_fma_f32 v[50:51], v[20:21], v[162:163], v[50:51] op_sel_hi:[1,0,1]
	v_pk_fma_f32 v[50:51], v[22:23], v[162:163], v[50:51] op_sel:[0,1,0] op_sel_hi:[1,1,1]
	s_nop 1
	v_add_f32_dpp v52, v51, v50 quad_perm:[1,0,3,2] row_mask:0xf bank_mask:0xf bound_ctrl:1
	ds_write_b32 v0, v52 offset:64512
